# NA bias softmax: the three blocks that issued 13-14 bias LDS reads up front now issue four and then one per element (lookahead 3) with recounted lgkmcnt waits, matching the faster fourth block
# speedup vs baseline: 1.0069x; 1.0069x over previous
; template <int DQK, bool NA, bool SMAX, int LDV> ...
;     ...
;         if (NA && it >= 4) {
;           const int kr = rs + (it - 4);
;           const int ql = w * 32 + qt * 16 + fr, qr = r0 + (ql >> 6), qc = ql & 63;
;           const int rst = min(max(qr - 4, 0), 24);
;           const bool rowok = (kr >= rst) && (kr < rst + 8);
;           const int cst = min(max(qc - 8, 0), 48);
;           const int base = (kr - qr + 7) * 31 + 15 - qc;
;           float bv[4][4];
; #pragma unroll
;           for (int kt = 0; kt < 4; ++kt)
; #pragma unroll
;             for (int j = 0; j < 4; ++j) bv[kt][j] = rpbl[min(max(base + kt * 16 + fq * 4 + j, 0), 464)];
; #pragma unroll
;           for (int kt = 0; kt < 4; ++kt)
; #pragma unroll
;             for (int j = 0; j < 4; ++j) {
;               const int kc = kt * 16 + fq * 4 + j;
;               const float okf = (rowok && (kc >= cst) && (kc < cst + 16)) ? 1.f : 0.f;
;               const float pv = __builtin_amdgcn_exp2f(__builtin_fmaf(s[kt][qt][j], c1, bv[kt][j] - m0)) * okf;
;               s[kt][qt][j] = pv; sum += pv;
;             }
.LBB0_1069:
	s_andn2_b64 vcc, exec, s[26:27]
	s_cbranch_vccnz .LBB0_1071
	v_subrev_u32_e32 v0, 31, v208
	s_movk_i32 s101, 0x100
	v_lshl_add_u32 v211, v0, 2, s101
	ds_read_b32 v104, v211 offset:41728
	ds_read_b32 v105, v211 offset:41732
	ds_read_b32 v106, v211 offset:41736
	ds_read_b32 v107, v211 offset:41740
	s_add_i32 s26, s19, s43
	s_add_i32 s26, s26, -4
	v_cmp_ge_i32_e32 vcc, s26, v164
	v_cmp_lt_i32_e64 s[40:41], s26, v163
	s_waitcnt lgkmcnt(3)
	s_or_b64 s[26:27], s[40:41], vcc
	v_fmac_f32_e32 v104, 0x3e38aa3b, v144
	ds_read_b32 v108, v211 offset:41792
	s_waitcnt lgkmcnt(3)
	s_or_b64 s[40:41], s[26:27], s[58:59]
	v_exp_f32_e32 v130, v104
	v_fmac_f32_e32 v105, 0x3e38aa3b, v145
	v_cndmask_b32_e64 v104, v130, 0, s[40:41]
	v_readlane_b32 s40, v248, 21
	v_exp_f32_e32 v131, v105
	v_readlane_b32 s41, v248, 22
	s_or_b64 s[40:41], s[26:27], s[40:41]
	ds_read_b32 v109, v211 offset:41796
	s_waitcnt lgkmcnt(3)
	v_mov_b32_e32 v0, v104
	v_cndmask_b32_e64 v105, v131, 0, s[40:41]
	v_fmac_f32_e32 v106, 0x3e38aa3b, v146
	v_add_f32_e32 v0, v0, v105
	v_exp_f32_e32 v131, v106
	s_or_b64 s[40:41], s[26:27], s[52:53]
	ds_read_b32 v110, v211 offset:41800
	s_waitcnt lgkmcnt(3)
	v_cndmask_b32_e64 v106, v131, 0, s[40:41]
	v_fmac_f32_e32 v107, 0x3e38aa3b, v147
	v_add_f32_e32 v0, v0, v106
	v_exp_f32_e32 v131, v107
	s_or_b64 s[40:41], s[26:27], s[54:55]
	ds_read_b32 v111, v211 offset:41804
	s_waitcnt lgkmcnt(3)
	v_cndmask_b32_e64 v107, v131, 0, s[40:41]
	v_fmac_f32_e32 v108, 0x3e38aa3b, v140
	v_add_f32_e32 v0, v0, v107
	v_exp_f32_e32 v131, v108
	s_or_b64 s[40:41], s[26:27], s[56:57]
	ds_read_b32 v112, v211 offset:41856
	s_waitcnt lgkmcnt(3)
	v_cndmask_b32_e64 v130, v165, 0, s[40:41]
	v_fmac_f32_e32 v109, 0x3e38aa3b, v141
	v_mul_f32_e32 v108, v130, v131
	v_fmac_f32_e32 v0, v130, v131
	v_exp_f32_e32 v131, v109
	s_or_b64 s[40:41], s[26:27], s[60:61]
	ds_read_b32 v113, v211 offset:41860
	s_waitcnt lgkmcnt(3)
	v_cndmask_b32_e64 v130, v166, 0, s[40:41]
	v_fmac_f32_e32 v110, 0x3e38aa3b, v142
	v_mul_f32_e32 v109, v130, v131
	v_fmac_f32_e32 v0, v130, v131
	v_exp_f32_e32 v131, v110
	s_or_b64 s[40:41], s[26:27], s[50:51]
	ds_read_b32 v114, v211 offset:41864
	s_waitcnt lgkmcnt(3)
	v_cndmask_b32_e64 v130, v168, 0, s[40:41]
	v_fmac_f32_e32 v111, 0x3e38aa3b, v143
	v_mul_f32_e32 v110, v130, v131
	v_fmac_f32_e32 v0, v130, v131
	v_exp_f32_e32 v131, v111
	s_or_b64 s[40:41], s[26:27], s[64:65]
	ds_read_b32 v115, v211 offset:41868
	s_waitcnt lgkmcnt(3)
	v_cndmask_b32_e64 v130, v169, 0, s[40:41]
	v_fmac_f32_e32 v112, 0x3e38aa3b, v136
	v_mul_f32_e32 v111, v130, v131
	v_fmac_f32_e32 v0, v130, v131
	v_exp_f32_e32 v131, v112
	s_or_b64 s[40:41], s[26:27], s[66:67]
	ds_read_b32 v128, v211 offset:41920
	s_waitcnt lgkmcnt(3)
	v_cndmask_b32_e64 v130, v170, 0, s[40:41]
	v_fmac_f32_e32 v113, 0x3e38aa3b, v137
	v_mul_f32_e32 v112, v130, v131
	v_fmac_f32_e32 v0, v130, v131
	v_exp_f32_e32 v131, v113
	s_or_b64 s[40:41], s[26:27], s[68:69]
	ds_read_b32 v129, v211 offset:41924
	s_waitcnt lgkmcnt(3)
	v_cndmask_b32_e64 v130, v171, 0, s[40:41]
	v_fmac_f32_e32 v114, 0x3e38aa3b, v138
	v_mul_f32_e32 v113, v130, v131
	v_fmac_f32_e32 v0, v130, v131
	v_exp_f32_e32 v131, v114
	s_or_b64 s[40:41], s[26:27], s[70:71]
	ds_read_b32 v2, v211 offset:41928
	s_waitcnt lgkmcnt(3)
	v_cndmask_b32_e64 v130, v172, 0, s[40:41]
	v_fmac_f32_e32 v115, 0x3e38aa3b, v139
	v_mul_f32_e32 v114, v130, v131
	v_fmac_f32_e32 v0, v130, v131
	v_exp_f32_e32 v131, v115
	s_or_b64 s[40:41], s[26:27], s[72:73]
	ds_read_b32 v3, v211 offset:41932
	s_waitcnt lgkmcnt(3)
	v_cndmask_b32_e64 v130, v173, 0, s[40:41]
	v_fmac_f32_e32 v128, 0x3e38aa3b, v132
	v_mul_f32_e32 v115, v130, v131
	v_fmac_f32_e32 v0, v130, v131
	v_exp_f32_e32 v131, v128
	s_waitcnt lgkmcnt(2)
	v_cndmask_b32_e64 v130, v174, 0, s[26:27]
	v_fmac_f32_e32 v129, 0x3e38aa3b, v133
	s_waitcnt lgkmcnt(1)
	v_mul_f32_e32 v128, v130, v131
	v_fmac_f32_e32 v0, v130, v131
	v_exp_f32_e32 v131, v129
	v_fmac_f32_e32 v2, 0x3e38aa3b, v134
	s_waitcnt lgkmcnt(0)
	v_exp_f32_e32 v2, v2
	v_fmac_f32_e32 v3, 0x3e38aa3b, v135
	v_exp_f32_e32 v3, v3
	v_cndmask_b32_e64 v130, v175, 0, s[26:27]
	v_mul_f32_e32 v129, v130, v131
	v_fmac_f32_e32 v0, v130, v131
	v_cndmask_b32_e64 v131, v176, 0, s[26:27]
	v_mul_f32_e32 v130, v131, v2
	v_fmac_f32_e32 v0, v131, v2
	v_cndmask_b32_e64 v2, v177, 0, s[26:27]
	v_mul_f32_e32 v131, v2, v3
	v_fmac_f32_e32 v0, v2, v3

; template <int DQK, bool NA, bool SMAX, int LDV> ...
;     ...
;         if (NA && it >= 4) {
;           const int kr = rs + (it - 4);
;           const int ql = w * 32 + qt * 16 + fr, qr = r0 + (ql >> 6), qc = ql & 63;
;           const int rst = min(max(qr - 4, 0), 24);
;           const bool rowok = (kr >= rst) && (kr < rst + 8);
;           const int cst = min(max(qc - 8, 0), 48);
;           const int base = (kr - qr + 7) * 31 + 15 - qc;
;           float bv[4][4];
; #pragma unroll
;           for (int kt = 0; kt < 4; ++kt)
; #pragma unroll
;             for (int j = 0; j < 4; ++j) bv[kt][j] = rpbl[min(max(base + kt * 16 + fq * 4 + j, 0), 464)];
; #pragma unroll
;           for (int kt = 0; kt < 4; ++kt)
; #pragma unroll
;             for (int j = 0; j < 4; ++j) {
;               const int kc = kt * 16 + fq * 4 + j;
;               const float okf = (rowok && (kc >= cst) && (kc < cst + 16)) ? 1.f : 0.f;
;               const float pv = __builtin_amdgcn_exp2f(__builtin_fmaf(s[kt][qt][j], c1, bv[kt][j] - m0)) * okf;
;               s[kt][qt][j] = pv; sum += pv;
;             }
.LBB0_1073:
	s_andn2_b64 vcc, exec, s[0:1]
	s_cbranch_vccnz .LBB0_1075
	v_subrev_u32_e32 v2, 47, v208
	s_movk_i32 s101, 0x100
	v_lshl_add_u32 v211, v2, 2, s101
	ds_read_b32 v132, v211 offset:41728
	ds_read_b32 v133, v211 offset:41732
	ds_read_b32 v134, v211 offset:41736
	ds_read_b32 v135, v211 offset:41740
	s_add_i32 s0, s19, s43
	s_waitcnt lgkmcnt(3)
	s_add_i32 s26, s0, -4
	v_fmac_f32_e32 v132, 0x3e38aa3b, v124
	ds_read_b32 v136, v211 offset:41792
	s_waitcnt lgkmcnt(3)
	v_cmp_ge_i32_e64 s[0:1], s26, v164
	v_cmp_lt_i32_e32 vcc, s26, v163
	v_exp_f32_e32 v124, v132
	v_fmac_f32_e32 v133, 0x3e38aa3b, v125
	s_or_b64 s[0:1], vcc, s[0:1]
	v_exp_f32_e32 v125, v133
	s_or_b64 s[26:27], s[0:1], s[82:83]
	v_cndmask_b32_e64 v132, v124, 0, s[26:27]
	s_or_b64 s[26:27], s[0:1], s[74:75]
	v_mov_b32_e32 v2, v132
	v_cndmask_b32_e64 v133, v125, 0, s[26:27]
	v_add_f32_e32 v2, v2, v133
	ds_read_b32 v137, v211 offset:41796
	s_waitcnt lgkmcnt(3)
	v_fma_f32 v125, v126, s62, v134
	v_exp_f32_e32 v125, v125
	s_or_b64 s[26:27], s[0:1], s[76:77]
	v_cndmask_b32_e64 v134, v125, 0, s[26:27]
	s_or_b64 s[26:27], s[0:1], s[78:79]
	v_add_f32_e32 v2, v2, v134
	ds_read_b32 v138, v211 offset:41800
	s_waitcnt lgkmcnt(3)
	v_fma_f32 v125, v127, s62, v135
	v_exp_f32_e32 v125, v125
	s_nop 0
	v_cndmask_b32_e64 v135, v125, 0, s[26:27]
	s_or_b64 s[26:27], s[0:1], s[80:81]
	ds_read_b32 v139, v211 offset:41804
	ds_read_b32 v140, v211 offset:41856
	ds_read_b32 v141, v211 offset:41860
	ds_read_b32 v142, v211 offset:41864
	ds_read_b32 v143, v211 offset:41868
	ds_read_b32 v144, v211 offset:41920
	ds_read_b32 v145, v211 offset:41924
	ds_read_b32 v3, v211 offset:41928
	ds_read_b32 v147, v211 offset:41932
	s_waitcnt lgkmcnt(1)
	v_add_f32_e32 v2, v2, v135
	v_fma_f32 v125, v120, s62, v136
	v_exp_f32_e32 v120, v125
	v_cndmask_b32_e64 v124, v178, 0, s[26:27]
	s_or_b64 s[26:27], s[0:1], s[84:85]
	v_fmac_f32_e32 v3, 0x3e38aa3b, v102
	v_mul_f32_e32 v136, v124, v120
	v_fmac_f32_e32 v2, v124, v120
	v_fma_f32 v124, v121, s62, v137
	v_exp_f32_e32 v121, v124
	v_cndmask_b32_e64 v120, v179, 0, s[26:27]
	s_or_b64 s[26:27], s[0:1], s[86:87]
	v_exp_f32_e32 v3, v3
	v_mul_f32_e32 v137, v120, v121
	v_fmac_f32_e32 v2, v120, v121
	v_fma_f32 v121, v122, s62, v138
	v_exp_f32_e32 v121, v121
	v_cndmask_b32_e64 v120, v180, 0, s[26:27]
	s_or_b64 s[26:27], s[0:1], s[88:89]
	v_mul_f32_e32 v138, v120, v121
	v_fmac_f32_e32 v2, v120, v121
	v_fma_f32 v121, v123, s62, v139
	v_exp_f32_e32 v121, v121
	v_cndmask_b32_e64 v120, v181, 0, s[26:27]
	s_or_b64 s[26:27], s[0:1], s[90:91]
	v_mul_f32_e32 v139, v120, v121
	v_fmac_f32_e32 v2, v120, v121
	v_fma_f32 v121, v116, s62, v140
	v_exp_f32_e32 v116, v121
	v_cndmask_b32_e64 v120, v182, 0, s[26:27]
	s_or_b64 s[26:27], s[0:1], s[92:93]
	v_mul_f32_e32 v140, v120, v116
	v_fmac_f32_e32 v2, v120, v116
	v_fma_f32 v120, v117, s62, v141
	v_exp_f32_e32 v117, v120
	v_cndmask_b32_e64 v116, v183, 0, s[26:27]
	s_or_b64 s[26:27], s[0:1], s[94:95]
	v_mul_f32_e32 v141, v116, v117
	v_fmac_f32_e32 v2, v116, v117
	v_fma_f32 v117, v118, s62, v142
	v_exp_f32_e32 v117, v117
	v_cndmask_b32_e64 v116, v184, 0, s[26:27]
	s_or_b64 s[26:27], s[0:1], s[96:97]
	v_mul_f32_e32 v142, v116, v117
	v_fmac_f32_e32 v2, v116, v117
	v_fma_f32 v117, v119, s62, v143
	v_exp_f32_e32 v117, v117
	v_cndmask_b32_e64 v116, v185, 0, s[26:27]
	v_mul_f32_e32 v143, v116, v117
	v_fmac_f32_e32 v2, v116, v117
	v_fma_f32 v117, v100, s62, v144
	v_exp_f32_e32 v100, v117
	v_cndmask_b32_e64 v116, v186, 0, s[0:1]
	v_mul_f32_e32 v144, v116, v100
	v_fmac_f32_e32 v2, v116, v100
	v_fma_f32 v116, v101, s62, v145
	v_exp_f32_e32 v101, v116
	v_cndmask_b32_e64 v100, v187, 0, s[0:1]
	v_mul_f32_e32 v145, v100, v101
	v_fmac_f32_e32 v2, v100, v101
	v_cndmask_b32_e64 v100, v189, 0, s[0:1]
	v_mul_f32_e32 v146, v100, v3
	v_fmac_f32_e32 v2, v100, v3
	s_waitcnt lgkmcnt(0)
	v_fma_f32 v100, v103, s62, v147
	v_exp_f32_e32 v100, v100
	v_cndmask_b32_e64 v3, v203, 0, s[0:1]
	v_mul_f32_e32 v147, v3, v100
	v_fmac_f32_e32 v2, v3, v100

; template <int DQK, bool NA, bool SMAX, int LDV> ...
;     ...
;         if (NA && it >= 4) {
;           const int kr = rs + (it - 4);
;           const int ql = w * 32 + qt * 16 + fr, qr = r0 + (ql >> 6), qc = ql & 63;
;           const int rst = min(max(qr - 4, 0), 24);
;           const bool rowok = (kr >= rst) && (kr < rst + 8);
;           const int cst = min(max(qc - 8, 0), 48);
;           const int base = (kr - qr + 7) * 31 + 15 - qc;
;           float bv[4][4];
; #pragma unroll
;           for (int kt = 0; kt < 4; ++kt)
; #pragma unroll
;             for (int j = 0; j < 4; ++j) bv[kt][j] = rpbl[min(max(base + kt * 16 + fq * 4 + j, 0), 464)];
; #pragma unroll
;           for (int kt = 0; kt < 4; ++kt)
; #pragma unroll
;             for (int j = 0; j < 4; ++j) {
;               const int kc = kt * 16 + fq * 4 + j;
;               const float okf = (rowok && (kc >= cst) && (kc < cst + 16)) ? 1.f : 0.f;
;               const float pv = __builtin_amdgcn_exp2f(__builtin_fmaf(s[kt][qt][j], c1, bv[kt][j] - m0)) * okf;
;               s[kt][qt][j] = pv; sum += pv;
;             }
.LBB0_1089:
	v_add_u32_e32 v2, -16, v208
	s_movk_i32 s101, 0x100
	v_lshl_add_u32 v211, v2, 2, s101
	ds_read_b32 v132, v211 offset:41728
	ds_read_b32 v133, v211 offset:41732
	ds_read_b32 v134, v211 offset:41736
	ds_read_b32 v135, v211 offset:41740
	s_add_i32 s0, s19, s43
	s_waitcnt lgkmcnt(3)
	s_add_i32 s0, s0, -3
	v_fmac_f32_e32 v132, 0x3e38aa3b, v124
	ds_read_b32 v136, v211 offset:41792
	s_waitcnt lgkmcnt(3)
	v_cmp_ge_i32_e32 vcc, s0, v164
	v_cmp_lt_i32_e64 s[0:1], s0, v163
	v_exp_f32_e32 v124, v132
	v_fmac_f32_e32 v133, 0x3e38aa3b, v125
	s_or_b64 s[0:1], s[0:1], vcc
	v_exp_f32_e32 v125, v133
	s_or_b64 s[26:27], s[0:1], s[82:83]
	v_cndmask_b32_e64 v132, v124, 0, s[26:27]
	s_or_b64 s[26:27], s[0:1], s[74:75]
	v_mov_b32_e32 v2, v132
	v_cndmask_b32_e64 v133, v125, 0, s[26:27]
	v_add_f32_e32 v2, v2, v133
	ds_read_b32 v137, v211 offset:41796
	s_waitcnt lgkmcnt(3)
	v_fma_f32 v125, v126, s62, v134
	v_exp_f32_e32 v125, v125
	s_or_b64 s[26:27], s[0:1], s[76:77]
	v_cndmask_b32_e64 v134, v125, 0, s[26:27]
	s_or_b64 s[26:27], s[0:1], s[78:79]
	v_add_f32_e32 v2, v2, v134
	ds_read_b32 v138, v211 offset:41800
	s_waitcnt lgkmcnt(3)
	v_fma_f32 v125, v127, s62, v135
	v_exp_f32_e32 v125, v125
	s_nop 0
	v_cndmask_b32_e64 v135, v125, 0, s[26:27]
	s_or_b64 s[26:27], s[0:1], s[80:81]
	ds_read_b32 v139, v211 offset:41804
	ds_read_b32 v140, v211 offset:41856
	ds_read_b32 v141, v211 offset:41860
	ds_read_b32 v142, v211 offset:41864
	ds_read_b32 v143, v211 offset:41868
	ds_read_b32 v144, v211 offset:41920
	ds_read_b32 v145, v211 offset:41924
	ds_read_b32 v3, v211 offset:41928
	ds_read_b32 v147, v211 offset:41932
	s_waitcnt lgkmcnt(1)
	v_add_f32_e32 v2, v2, v135
	v_fma_f32 v125, v120, s62, v136
	v_exp_f32_e32 v120, v125
	v_cndmask_b32_e64 v124, v178, 0, s[26:27]
	s_or_b64 s[26:27], s[0:1], s[84:85]
	v_fmac_f32_e32 v3, 0x3e38aa3b, v102
	v_mul_f32_e32 v136, v124, v120
	v_fmac_f32_e32 v2, v124, v120
	v_fma_f32 v124, v121, s62, v137
	v_exp_f32_e32 v121, v124
	v_cndmask_b32_e64 v120, v179, 0, s[26:27]
	s_or_b64 s[26:27], s[0:1], s[86:87]
	v_exp_f32_e32 v3, v3
	v_mul_f32_e32 v137, v120, v121
	v_fmac_f32_e32 v2, v120, v121
	v_fma_f32 v121, v122, s62, v138
	v_exp_f32_e32 v121, v121
	v_cndmask_b32_e64 v120, v180, 0, s[26:27]
	s_or_b64 s[26:27], s[0:1], s[88:89]
	v_mul_f32_e32 v138, v120, v121
	v_fmac_f32_e32 v2, v120, v121
	v_fma_f32 v121, v123, s62, v139
	v_exp_f32_e32 v121, v121
	v_cndmask_b32_e64 v120, v181, 0, s[26:27]
	s_or_b64 s[26:27], s[0:1], s[90:91]
	v_mul_f32_e32 v139, v120, v121
	v_fmac_f32_e32 v2, v120, v121
	v_fma_f32 v121, v116, s62, v140
	v_exp_f32_e32 v116, v121
	v_cndmask_b32_e64 v120, v182, 0, s[26:27]
	s_or_b64 s[26:27], s[0:1], s[92:93]
	v_mul_f32_e32 v140, v120, v116
	v_fmac_f32_e32 v2, v120, v116
	v_fma_f32 v120, v117, s62, v141
	v_exp_f32_e32 v117, v120
	v_cndmask_b32_e64 v116, v183, 0, s[26:27]
	s_or_b64 s[26:27], s[0:1], s[94:95]
	v_mul_f32_e32 v141, v116, v117
	v_fmac_f32_e32 v2, v116, v117
	v_fma_f32 v117, v118, s62, v142
	v_exp_f32_e32 v117, v117
	v_cndmask_b32_e64 v116, v184, 0, s[26:27]
	s_or_b64 s[26:27], s[0:1], s[96:97]
	v_mul_f32_e32 v142, v116, v117
	v_fmac_f32_e32 v2, v116, v117
	v_fma_f32 v117, v119, s62, v143
	v_exp_f32_e32 v117, v117
	v_cndmask_b32_e64 v116, v185, 0, s[26:27]
	v_mul_f32_e32 v143, v116, v117
	v_fmac_f32_e32 v2, v116, v117
	v_fma_f32 v117, v100, s62, v144
	v_exp_f32_e32 v100, v117
	v_cndmask_b32_e64 v116, v186, 0, s[0:1]
	v_mul_f32_e32 v144, v116, v100
	v_fmac_f32_e32 v2, v116, v100
	v_fma_f32 v116, v101, s62, v145
	v_exp_f32_e32 v101, v116
	v_cndmask_b32_e64 v100, v187, 0, s[0:1]
	v_mul_f32_e32 v145, v100, v101
	v_fmac_f32_e32 v2, v100, v101
	v_cndmask_b32_e64 v100, v189, 0, s[0:1]
	v_mul_f32_e32 v146, v100, v3
	v_fmac_f32_e32 v2, v100, v3
	s_waitcnt lgkmcnt(0)
	v_fma_f32 v100, v103, s62, v147
	v_exp_f32_e32 v100, v100
	v_cndmask_b32_e64 v3, v203, 0, s[0:1]
	v_mul_f32_e32 v147, v3, v100
	v_fmac_f32_e32 v2, v3, v100
